# in-projection: the two workgroups of a CU also alternate issue priority round by round (kept through the tile epilogue), on top of the attention alternation
# speedup vs baseline: 1.0187x; 1.0037x over previous
.LBB0_243:
	s_lshl_b64 s[0:1], s[18:19], 18
	s_add_u32 s76, s4, s0
	s_addc_u32 s77, s5, s1
	s_mov_b32 s43, s19
	s_lshl_b64 s[16:17], s[42:43], 18
	s_add_u32 s36, s60, s16
	s_addc_u32 s37, s49, s17
	s_mov_b32 s78, s36
	s_mov_b32 s79, s37
	v_lshrrev_b32_e32 v96, 3, v138
	v_bfe_u32 v97, v138, 4, 3
	v_and_b32_e32 v98, 7, v138
	v_xor_b32_e32 v97, v97, v98
	v_lshlrev_b32_e32 v97, 4, v97
	v_lshl_add_u32 v240, v96, 11, v97
	v_add_u32_e32 v241, 0x10000, v240
	v_add_u32_e32 v242, 0x20000, v240
	v_add_u32_e32 v243, 0x30000, v240
	v_lshrrev_b32_e32 v99, 6, v138
	s_nop 0
	v_readfirstlane_b32 s80, v99
	s_lshl_b32 s81, s80, 10
	s_getreg_b32 s0, hwreg(HW_REG_LDS_ALLOC, 0, 8)
	s_cmp_lg_u32 s0, 0
	s_cselect_b32 s0, 1, 0
	s_lshr_b32 s1, s96, 3
	s_sub_u32 s1, s58, s1
	s_and_b32 s2, s96, 7
	s_mul_i32 s2, s2, 0x16b
	s_sub_u32 s1, s1, s2
	s_lshr_b32 s1, s1, 6
	s_xor_b32 s0, s0, s1
	s_bitcmp1_b32 s0, 0
	s_cbranch_scc1 .Lip_prhi
	s_setprio 0
	s_branch .Lip_prdone

.Lip_prdone:
	s_barrier
	s_add_i32 m0, s81, 0
	s_nop 0
	global_load_lds_dwordx4 v240, s[76:77]
	s_add_i32 m0, s81, 4096
	s_nop 0
	global_load_lds_dwordx4 v241, s[76:77]
	s_add_i32 m0, s81, 8192
	s_nop 0
	global_load_lds_dwordx4 v242, s[76:77]
	s_add_i32 m0, s81, 12288
	s_nop 0
	global_load_lds_dwordx4 v243, s[76:77]
	s_add_i32 m0, s81, 16384
	s_nop 0
	global_load_lds_dwordx4 v240, s[78:79]
	s_add_i32 m0, s81, 20480
	s_nop 0
	global_load_lds_dwordx4 v241, s[78:79]
	s_add_i32 m0, s81, 24576
	s_nop 0
	global_load_lds_dwordx4 v242, s[78:79]
	s_add_i32 m0, s81, 28672
	s_nop 0
	global_load_lds_dwordx4 v243, s[78:79]
	s_add_u32 s76, s76, 0x80
	s_addc_u32 s77, s77, 0
	s_add_u32 s78, s78, 0x80
	s_addc_u32 s79, s79, 0
	v_and_b32_e32 v100, 15, v138
	v_bfe_u32 v101, v138, 4, 2
	v_lshrrev_b32_e32 v102, 1, v100
	v_xor_b32_e32 v102, v102, v101
	v_lshlrev_b32_e32 v102, 4, v102
	v_lshrrev_b32_e32 v103, 1, v99
	v_and_b32_e32 v99, 1, v99
	v_lshl_add_u32 v96, v103, 6, v100
	v_lshl_add_u32 v244, v96, 7, v102
	v_xor_b32_e32 v245, 64, v244
	v_lshl_add_u32 v96, v99, 6, v100
	v_lshl_add_u32 v246, v96, 7, v102
	v_add_u32_e32 v246, 0x4000, v246
	v_xor_b32_e32 v247, 64, v246
	v_lshlrev_b32_e32 v96, 6, v103
	v_lshl_add_u32 v96, v101, 2, v96
	s_movk_i32 s0, 0x210
	v_mul_lo_u32 v96, v96, s0
	v_lshl_add_u32 v97, v99, 6, v100
	v_lshl_add_u32 v248, v97, 2, v96
	s_movk_i32 s82, 7
	s_waitcnt vmcnt(0)
	s_barrier
	ds_read_b128 v[64:67], v244 offset:0
	ds_read_b128 v[80:83], v246 offset:0
	ds_read_b128 v[84:87], v246 offset:2048
	ds_read_b128 v[88:91], v246 offset:4096
	ds_read_b128 v[92:95], v246 offset:6144
	ds_read_b128 v[68:71], v244 offset:2048
	ds_read_b128 v[72:75], v244 offset:4096
	ds_read_b128 v[76:79], v244 offset:6144
	s_waitcnt lgkmcnt(6)
	v_mfma_f32_16x16x32_bf16 v[0:3], v[64:67], v[80:83], 0
	ds_read_b128 v[208:211], v245 offset:0
	s_add_i32 m0, s81, 32768
	s_waitcnt lgkmcnt(6)
	v_mfma_f32_16x16x32_bf16 v[4:7], v[64:67], v[84:87], 0
	ds_read_b128 v[224:227], v247 offset:0
	global_load_lds_dwordx4 v240, s[76:77]
	s_waitcnt lgkmcnt(6)
	v_mfma_f32_16x16x32_bf16 v[8:11], v[64:67], v[88:91], 0
	ds_read_b128 v[228:231], v247 offset:2048
	s_add_i32 m0, s81, 36864
	s_waitcnt lgkmcnt(6)
	v_mfma_f32_16x16x32_bf16 v[12:15], v[64:67], v[92:95], 0
	ds_read_b128 v[232:235], v247 offset:4096
	global_load_lds_dwordx4 v241, s[76:77]
	s_waitcnt lgkmcnt(6)
	v_mfma_f32_16x16x32_bf16 v[16:19], v[68:71], v[80:83], 0
	ds_read_b128 v[236:239], v247 offset:6144
	s_add_i32 m0, s81, 40960
	v_mfma_f32_16x16x32_bf16 v[20:23], v[68:71], v[84:87], 0
	ds_read_b128 v[212:215], v245 offset:2048
	global_load_lds_dwordx4 v242, s[76:77]
	v_mfma_f32_16x16x32_bf16 v[24:27], v[68:71], v[88:91], 0
	ds_read_b128 v[216:219], v245 offset:4096
	s_add_i32 m0, s81, 45056
	v_mfma_f32_16x16x32_bf16 v[28:31], v[68:71], v[92:95], 0
	ds_read_b128 v[220:223], v245 offset:6144
	global_load_lds_dwordx4 v243, s[76:77]
	s_waitcnt lgkmcnt(9)
	v_mfma_f32_16x16x32_bf16 v[32:35], v[72:75], v[80:83], 0
	s_add_i32 m0, s81, 49152
	v_mfma_f32_16x16x32_bf16 v[36:39], v[72:75], v[84:87], 0
	global_load_lds_dwordx4 v240, s[78:79]
	v_mfma_f32_16x16x32_bf16 v[40:43], v[72:75], v[88:91], 0
	s_add_i32 m0, s81, 53248
	v_mfma_f32_16x16x32_bf16 v[44:47], v[72:75], v[92:95], 0
	global_load_lds_dwordx4 v241, s[78:79]
	s_waitcnt lgkmcnt(8)
	v_mfma_f32_16x16x32_bf16 v[48:51], v[76:79], v[80:83], 0
	s_add_i32 m0, s81, 57344
	v_mfma_f32_16x16x32_bf16 v[52:55], v[76:79], v[84:87], 0
	global_load_lds_dwordx4 v242, s[78:79]
	v_mfma_f32_16x16x32_bf16 v[56:59], v[76:79], v[88:91], 0
	s_add_i32 m0, s81, 61440
	v_mfma_f32_16x16x32_bf16 v[60:63], v[76:79], v[92:95], 0
	global_load_lds_dwordx4 v243, s[78:79]
	s_waitcnt lgkmcnt(6)
	v_mfma_f32_16x16x32_bf16 v[0:3], v[208:211], v[224:227], v[0:3]
	s_add_u32 s76, s76, 0x80
	s_addc_u32 s77, s77, 0
	s_waitcnt lgkmcnt(5)
	v_mfma_f32_16x16x32_bf16 v[4:7], v[208:211], v[228:231], v[4:7]
	s_waitcnt lgkmcnt(4)
	v_mfma_f32_16x16x32_bf16 v[8:11], v[208:211], v[232:235], v[8:11]
	s_add_u32 s78, s78, 0x80
	s_addc_u32 s79, s79, 0
	s_waitcnt lgkmcnt(3)
	v_mfma_f32_16x16x32_bf16 v[12:15], v[208:211], v[236:239], v[12:15]
	s_waitcnt lgkmcnt(2)
	v_mfma_f32_16x16x32_bf16 v[16:19], v[212:215], v[224:227], v[16:19]
	v_mfma_f32_16x16x32_bf16 v[20:23], v[212:215], v[228:231], v[20:23]
	v_mfma_f32_16x16x32_bf16 v[24:27], v[212:215], v[232:235], v[24:27]
	v_mfma_f32_16x16x32_bf16 v[28:31], v[212:215], v[236:239], v[28:31]
	s_waitcnt lgkmcnt(1)
	v_mfma_f32_16x16x32_bf16 v[32:35], v[216:219], v[224:227], v[32:35]
	v_mfma_f32_16x16x32_bf16 v[36:39], v[216:219], v[228:231], v[36:39]
	v_mfma_f32_16x16x32_bf16 v[40:43], v[216:219], v[232:235], v[40:43]
	v_mfma_f32_16x16x32_bf16 v[44:47], v[216:219], v[236:239], v[44:47]
	s_waitcnt lgkmcnt(0)
	v_mfma_f32_16x16x32_bf16 v[48:51], v[220:223], v[224:227], v[48:51]
	v_mfma_f32_16x16x32_bf16 v[52:55], v[220:223], v[228:231], v[52:55]
	v_mfma_f32_16x16x32_bf16 v[56:59], v[220:223], v[232:235], v[56:59]
	v_mfma_f32_16x16x32_bf16 v[60:63], v[220:223], v[236:239], v[60:63]
	s_waitcnt vmcnt(0)
	s_barrier
	ds_read_b128 v[64:67], v244 offset:32768
	ds_read_b128 v[80:83], v246 offset:32768
	ds_read_b128 v[84:87], v246 offset:34816
	ds_read_b128 v[88:91], v246 offset:36864
	ds_read_b128 v[92:95], v246 offset:38912
	ds_read_b128 v[68:71], v244 offset:34816
	ds_read_b128 v[72:75], v244 offset:36864
	ds_read_b128 v[76:79], v244 offset:38912
	s_waitcnt lgkmcnt(6)
	v_mfma_f32_16x16x32_bf16 v[0:3], v[64:67], v[80:83], v[0:3]
	ds_read_b128 v[208:211], v245 offset:32768
	s_add_i32 m0, s81, 0
	s_waitcnt lgkmcnt(6)
	v_mfma_f32_16x16x32_bf16 v[4:7], v[64:67], v[84:87], v[4:7]
	ds_read_b128 v[224:227], v247 offset:32768
	global_load_lds_dwordx4 v240, s[76:77]
	s_waitcnt lgkmcnt(6)
	v_mfma_f32_16x16x32_bf16 v[8:11], v[64:67], v[88:91], v[8:11]
	ds_read_b128 v[228:231], v247 offset:34816
	s_add_i32 m0, s81, 4096
	s_waitcnt lgkmcnt(6)
	v_mfma_f32_16x16x32_bf16 v[12:15], v[64:67], v[92:95], v[12:15]
	ds_read_b128 v[232:235], v247 offset:36864
	global_load_lds_dwordx4 v241, s[76:77]
	s_waitcnt lgkmcnt(6)
	v_mfma_f32_16x16x32_bf16 v[16:19], v[68:71], v[80:83], v[16:19]
	ds_read_b128 v[236:239], v247 offset:38912
	s_add_i32 m0, s81, 8192
	v_mfma_f32_16x16x32_bf16 v[20:23], v[68:71], v[84:87], v[20:23]
	ds_read_b128 v[212:215], v245 offset:34816
	global_load_lds_dwordx4 v242, s[76:77]
	v_mfma_f32_16x16x32_bf16 v[24:27], v[68:71], v[88:91], v[24:27]
	ds_read_b128 v[216:219], v245 offset:36864
	s_add_i32 m0, s81, 12288
	v_mfma_f32_16x16x32_bf16 v[28:31], v[68:71], v[92:95], v[28:31]
	ds_read_b128 v[220:223], v245 offset:38912
	global_load_lds_dwordx4 v243, s[76:77]
	s_waitcnt lgkmcnt(9)
	v_mfma_f32_16x16x32_bf16 v[32:35], v[72:75], v[80:83], v[32:35]
	s_add_i32 m0, s81, 16384
	v_mfma_f32_16x16x32_bf16 v[36:39], v[72:75], v[84:87], v[36:39]
	global_load_lds_dwordx4 v240, s[78:79]
	v_mfma_f32_16x16x32_bf16 v[40:43], v[72:75], v[88:91], v[40:43]
	s_add_i32 m0, s81, 20480
	v_mfma_f32_16x16x32_bf16 v[44:47], v[72:75], v[92:95], v[44:47]
	global_load_lds_dwordx4 v241, s[78:79]
	s_waitcnt lgkmcnt(8)
	v_mfma_f32_16x16x32_bf16 v[48:51], v[76:79], v[80:83], v[48:51]
	s_add_i32 m0, s81, 24576
	v_mfma_f32_16x16x32_bf16 v[52:55], v[76:79], v[84:87], v[52:55]
	global_load_lds_dwordx4 v242, s[78:79]
	v_mfma_f32_16x16x32_bf16 v[56:59], v[76:79], v[88:91], v[56:59]
	s_add_i32 m0, s81, 28672
	v_mfma_f32_16x16x32_bf16 v[60:63], v[76:79], v[92:95], v[60:63]
	global_load_lds_dwordx4 v243, s[78:79]
	s_waitcnt lgkmcnt(6)
	v_mfma_f32_16x16x32_bf16 v[0:3], v[208:211], v[224:227], v[0:3]
	s_add_u32 s76, s76, 0x80
	s_addc_u32 s77, s77, 0
	s_waitcnt lgkmcnt(5)
	v_mfma_f32_16x16x32_bf16 v[4:7], v[208:211], v[228:231], v[4:7]
	s_waitcnt lgkmcnt(4)
	v_mfma_f32_16x16x32_bf16 v[8:11], v[208:211], v[232:235], v[8:11]
	s_add_u32 s78, s78, 0x80
	s_addc_u32 s79, s79, 0
	s_waitcnt lgkmcnt(3)
	v_mfma_f32_16x16x32_bf16 v[12:15], v[208:211], v[236:239], v[12:15]
	s_waitcnt lgkmcnt(2)
	v_mfma_f32_16x16x32_bf16 v[16:19], v[212:215], v[224:227], v[16:19]
	v_mfma_f32_16x16x32_bf16 v[20:23], v[212:215], v[228:231], v[20:23]
	v_mfma_f32_16x16x32_bf16 v[24:27], v[212:215], v[232:235], v[24:27]
	v_mfma_f32_16x16x32_bf16 v[28:31], v[212:215], v[236:239], v[28:31]
	s_waitcnt lgkmcnt(1)
	v_mfma_f32_16x16x32_bf16 v[32:35], v[216:219], v[224:227], v[32:35]
	v_mfma_f32_16x16x32_bf16 v[36:39], v[216:219], v[228:231], v[36:39]
	v_mfma_f32_16x16x32_bf16 v[40:43], v[216:219], v[232:235], v[40:43]
	v_mfma_f32_16x16x32_bf16 v[44:47], v[216:219], v[236:239], v[44:47]
	s_waitcnt lgkmcnt(0)
	v_mfma_f32_16x16x32_bf16 v[48:51], v[220:223], v[224:227], v[48:51]
	v_mfma_f32_16x16x32_bf16 v[52:55], v[220:223], v[228:231], v[52:55]
	v_mfma_f32_16x16x32_bf16 v[56:59], v[220:223], v[232:235], v[56:59]
	v_mfma_f32_16x16x32_bf16 v[60:63], v[220:223], v[236:239], v[60:63]
	s_movk_i32 s82, 6

.LBB0_294:
	s_setprio 0
	s_waitcnt vmcnt(0)
	s_barrier
	s_mov_b64 s[0:1], exec
	v_readlane_b32 s2, v207, 0
	v_readlane_b32 s3, v207, 1
	v_readlane_b32 s58, v205, 12
	s_and_b64 s[2:3], s[0:1], s[2:3]
	v_readlane_b32 s59, v205, 13
	s_movk_i32 s20, 0x4200
	v_readlane_b32 s8, v205, 18
	s_mov_b64 exec, s[2:3]
	s_cbranch_execz .LBB0_342
	s_waitcnt vmcnt(0) expcnt(0) lgkmcnt(0)
	ds_read_b32 v2, v140
	ds_read_b32 v0, v141
	s_waitcnt lgkmcnt(1)
	v_cmp_ne_u32_e32 vcc, 0, v2
	s_cbranch_vccnz .LBB0_310
	v_readlane_b32 s12, v207, 52
	v_readlane_b32 s13, v207, 53
	s_load_dwordx2 s[2:3], s[12:13], 0x4
	s_mov_b32 s36, 1
	s_waitcnt lgkmcnt(0)
	s_mul_i32 s18, s2, s8
	s_mul_i32 s18, s18, s3
	s_branch .LBB0_298
